# B item epilogue widened: O*rl transposed through a wave-private f32 LDS tile, gate read-modify-write of G with 16-byte row-contiguous loads/stores (8+8 per lane) instead of 64+64 two-byte accesses
# speedup vs baseline: 1.0185x; 1.0028x over previous
.LBB0_366:
	s_or_b64 exec, exec, s[18:19]
	s_ashr_i32 s18, s63, 31
	s_add_u32 s2, s2, s63
	s_addc_u32 s3, s3, s18
	v_ashrrev_i32_e32 v145, 31, v144
	v_lshl_add_u64 v[64:65], s[2:3], 0, v[144:145]
	v_lshlrev_b64 v[64:65], 11, v[64:65]
	v_lshl_add_u64 v[64:65], s[4:5], 0, v[64:65]
	s_lshl_b32 s22, s64, 1
	v_lshl_add_u64 v[64:65], v[64:65], 0, s[22:23]
	v_lshlrev_b32_e32 v184, 1, v157
	v_lshl_add_u64 v[64:65], v[64:65], 0, v[184:185]
	s_mov_b64 s[2:3], 0x7000400
	v_lshl_add_u64 v[64:65], v[64:65], 0, s[2:3]
	v_lshlrev_b32_e32 v184, 13, v156
	s_waitcnt lgkmcnt(0)
	v_lshl_add_u64 v[68:69], v[64:65], 0, v[184:185]
	v_lshl_add_u32 v66, v156, 4, v66
	ds_read_b32 v70, v66 offset:0
	ds_read_b32 v71, v66 offset:4
	ds_read_b32 v72, v66 offset:8
	ds_read_b32 v73, v66 offset:12
	ds_read_b32 v74, v66 offset:32
	ds_read_b32 v75, v66 offset:36
	ds_read_b32 v76, v66 offset:40
	ds_read_b32 v77, v66 offset:44
	ds_read_b32 v78, v66 offset:64
	ds_read_b32 v79, v66 offset:68
	ds_read_b32 v80, v66 offset:72
	ds_read_b32 v81, v66 offset:76
	ds_read_b32 v82, v66 offset:96
	ds_read_b32 v83, v66 offset:100
	ds_read_b32 v84, v66 offset:104
	ds_read_b32 v85, v66 offset:108
	v_readfirstlane_b32 s2, v64
	v_readfirstlane_b32 s3, v65
	v_lshl_or_b32 v67, v156, 5, v157
	v_lshrrev_b32_e32 v68, 4, v67
	v_and_b32_e32 v69, 15, v67
	v_lshlrev_b32_e32 v86, 11, v68
	v_lshl_or_b32 v86, v69, 4, v86
	s_sub_u32 s18, s100, 0x8000
	s_lshl_b32 s18, s18, 4
	v_lshlrev_b32_e32 v87, 11, v156
	v_lshl_or_b32 v87, v157, 2, v87
	v_add_u32_e32 v87, s18, v87
	v_lshlrev_b32_e32 v88, 9, v68
	v_lshl_or_b32 v88, v69, 5, v88
	v_add_u32_e32 v88, s18, v88
	global_load_dwordx4 v[96:99], v86, s[2:3]
	s_add_u32 s2, s2, 0x2000
	s_addc_u32 s3, s3, 0
	global_load_dwordx4 v[100:103], v86, s[2:3]
	s_add_u32 s2, s2, 0x2000
	s_addc_u32 s3, s3, 0
	global_load_dwordx4 v[104:107], v86, s[2:3]
	s_add_u32 s2, s2, 0x2000
	s_addc_u32 s3, s3, 0
	global_load_dwordx4 v[108:111], v86, s[2:3]
	s_add_u32 s2, s2, 0x2000
	s_addc_u32 s3, s3, 0
	global_load_dwordx4 v[112:115], v86, s[2:3]
	s_add_u32 s2, s2, 0x2000
	s_addc_u32 s3, s3, 0
	global_load_dwordx4 v[116:119], v86, s[2:3]
	s_add_u32 s2, s2, 0x2000
	s_addc_u32 s3, s3, 0
	global_load_dwordx4 v[120:123], v86, s[2:3]
	s_add_u32 s2, s2, 0x2000
	s_addc_u32 s3, s3, 0
	global_load_dwordx4 v[124:127], v86, s[2:3]
	s_sub_u32 s2, s2, 0xe000
	s_subb_u32 s3, s3, 0
	s_waitcnt lgkmcnt(0)
	v_mul_f32_e32 v48, v48, v70
	v_mul_f32_e32 v32, v32, v70
	v_mul_f32_e32 v16, v16, v70
	v_mul_f32_e32 v0, v0, v70
	ds_write_b32 v87, v48 offset:0
	ds_write_b32 v87, v32 offset:128
	ds_write_b32 v87, v16 offset:256
	ds_write_b32 v87, v0 offset:384
	v_mul_f32_e32 v49, v49, v71
	v_mul_f32_e32 v33, v33, v71
	v_mul_f32_e32 v17, v17, v71
	v_mul_f32_e32 v1, v1, v71
	ds_write_b32 v87, v49 offset:512
	ds_write_b32 v87, v33 offset:640
	ds_write_b32 v87, v17 offset:768
	ds_write_b32 v87, v1 offset:896
	v_mul_f32_e32 v50, v50, v72
	v_mul_f32_e32 v34, v34, v72
	v_mul_f32_e32 v18, v18, v72
	v_mul_f32_e32 v2, v2, v72
	ds_write_b32 v87, v50 offset:1024
	ds_write_b32 v87, v34 offset:1152
	ds_write_b32 v87, v18 offset:1280
	ds_write_b32 v87, v2 offset:1408
	v_mul_f32_e32 v51, v51, v73
	v_mul_f32_e32 v35, v35, v73
	v_mul_f32_e32 v19, v19, v73
	v_mul_f32_e32 v3, v3, v73
	ds_write_b32 v87, v51 offset:1536
	ds_write_b32 v87, v35 offset:1664
	ds_write_b32 v87, v19 offset:1792
	ds_write_b32 v87, v3 offset:1920
	v_mul_f32_e32 v52, v52, v74
	v_mul_f32_e32 v36, v36, v74
	v_mul_f32_e32 v20, v20, v74
	v_mul_f32_e32 v4, v4, v74
	ds_write_b32 v87, v52 offset:4096
	ds_write_b32 v87, v36 offset:4224
	ds_write_b32 v87, v20 offset:4352
	ds_write_b32 v87, v4 offset:4480
	v_mul_f32_e32 v53, v53, v75
	v_mul_f32_e32 v37, v37, v75
	v_mul_f32_e32 v21, v21, v75
	v_mul_f32_e32 v5, v5, v75
	ds_write_b32 v87, v53 offset:4608
	ds_write_b32 v87, v37 offset:4736
	ds_write_b32 v87, v21 offset:4864
	ds_write_b32 v87, v5 offset:4992
	v_mul_f32_e32 v54, v54, v76
	v_mul_f32_e32 v38, v38, v76
	v_mul_f32_e32 v22, v22, v76
	v_mul_f32_e32 v6, v6, v76
	ds_write_b32 v87, v54 offset:5120
	ds_write_b32 v87, v38 offset:5248
	ds_write_b32 v87, v22 offset:5376
	ds_write_b32 v87, v6 offset:5504
	v_mul_f32_e32 v55, v55, v77
	v_mul_f32_e32 v39, v39, v77
	v_mul_f32_e32 v23, v23, v77
	v_mul_f32_e32 v7, v7, v77
	ds_write_b32 v87, v55 offset:5632
	ds_write_b32 v87, v39 offset:5760
	ds_write_b32 v87, v23 offset:5888
	ds_write_b32 v87, v7 offset:6016
	v_mul_f32_e32 v56, v56, v78
	v_mul_f32_e32 v40, v40, v78
	v_mul_f32_e32 v24, v24, v78
	v_mul_f32_e32 v8, v8, v78
	ds_write_b32 v87, v56 offset:8192
	ds_write_b32 v87, v40 offset:8320
	ds_write_b32 v87, v24 offset:8448
	ds_write_b32 v87, v8 offset:8576
	v_mul_f32_e32 v57, v57, v79
	v_mul_f32_e32 v41, v41, v79
	v_mul_f32_e32 v25, v25, v79
	v_mul_f32_e32 v9, v9, v79
	ds_write_b32 v87, v57 offset:8704
	ds_write_b32 v87, v41 offset:8832
	ds_write_b32 v87, v25 offset:8960
	ds_write_b32 v87, v9 offset:9088
	v_mul_f32_e32 v58, v58, v80
	v_mul_f32_e32 v42, v42, v80
	v_mul_f32_e32 v26, v26, v80
	v_mul_f32_e32 v10, v10, v80
	ds_write_b32 v87, v58 offset:9216
	ds_write_b32 v87, v42 offset:9344
	ds_write_b32 v87, v26 offset:9472
	ds_write_b32 v87, v10 offset:9600
	v_mul_f32_e32 v59, v59, v81
	v_mul_f32_e32 v43, v43, v81
	v_mul_f32_e32 v27, v27, v81
	v_mul_f32_e32 v11, v11, v81
	ds_write_b32 v87, v59 offset:9728
	ds_write_b32 v87, v43 offset:9856
	ds_write_b32 v87, v27 offset:9984
	ds_write_b32 v87, v11 offset:10112
	v_mul_f32_e32 v60, v60, v82
	v_mul_f32_e32 v44, v44, v82
	v_mul_f32_e32 v28, v28, v82
	v_mul_f32_e32 v12, v12, v82
	ds_write_b32 v87, v60 offset:12288
	ds_write_b32 v87, v44 offset:12416
	ds_write_b32 v87, v28 offset:12544
	ds_write_b32 v87, v12 offset:12672
	v_mul_f32_e32 v61, v61, v83
	v_mul_f32_e32 v45, v45, v83
	v_mul_f32_e32 v29, v29, v83
	v_mul_f32_e32 v13, v13, v83
	ds_write_b32 v87, v61 offset:12800
	ds_write_b32 v87, v45 offset:12928
	ds_write_b32 v87, v29 offset:13056
	ds_write_b32 v87, v13 offset:13184
	v_mul_f32_e32 v62, v62, v84
	v_mul_f32_e32 v46, v46, v84
	v_mul_f32_e32 v30, v30, v84
	v_mul_f32_e32 v14, v14, v84
	ds_write_b32 v87, v62 offset:13312
	ds_write_b32 v87, v46 offset:13440
	ds_write_b32 v87, v30 offset:13568
	ds_write_b32 v87, v14 offset:13696
	v_mul_f32_e32 v63, v63, v85
	v_mul_f32_e32 v47, v47, v85
	v_mul_f32_e32 v31, v31, v85
	v_mul_f32_e32 v15, v15, v85
	ds_write_b32 v87, v63 offset:13824
	ds_write_b32 v87, v47 offset:13952
	ds_write_b32 v87, v31 offset:14080
	ds_write_b32 v87, v15 offset:14208
	ds_read_b128 v[0:3], v88 offset:0
	ds_read_b128 v[4:7], v88 offset:16
	ds_read_b128 v[8:11], v88 offset:2048
	ds_read_b128 v[12:15], v88 offset:2064
	ds_read_b128 v[16:19], v88 offset:4096
	ds_read_b128 v[20:23], v88 offset:4112
	ds_read_b128 v[24:27], v88 offset:6144
	ds_read_b128 v[28:31], v88 offset:6160
	ds_read_b128 v[32:35], v88 offset:8192
	ds_read_b128 v[36:39], v88 offset:8208
	ds_read_b128 v[40:43], v88 offset:10240
	ds_read_b128 v[44:47], v88 offset:10256
	ds_read_b128 v[48:51], v88 offset:12288
	ds_read_b128 v[52:55], v88 offset:12304
	ds_read_b128 v[56:59], v88 offset:14336
	ds_read_b128 v[60:63], v88 offset:14352
	s_waitcnt vmcnt(0) lgkmcnt(0)
	v_lshlrev_b32_e32 v89, 16, v96
	v_mul_f32_e32 v0, v0, v89
	v_and_b32_e32 v89, 0xffff0000, v96
	v_mul_f32_e32 v1, v1, v89
	v_lshlrev_b32_e32 v89, 16, v97
	v_mul_f32_e32 v2, v2, v89
	v_and_b32_e32 v89, 0xffff0000, v97
	v_mul_f32_e32 v3, v3, v89
	v_lshlrev_b32_e32 v89, 16, v98
	v_mul_f32_e32 v4, v4, v89
	v_and_b32_e32 v89, 0xffff0000, v98
	v_mul_f32_e32 v5, v5, v89
	v_lshlrev_b32_e32 v89, 16, v99
	v_mul_f32_e32 v6, v6, v89
	v_and_b32_e32 v89, 0xffff0000, v99
	v_mul_f32_e32 v7, v7, v89
	v_cvt_pk_bf16_f32 v128, v0, v1
	v_cvt_pk_bf16_f32 v129, v2, v3
	v_cvt_pk_bf16_f32 v130, v4, v5
	v_cvt_pk_bf16_f32 v131, v6, v7
	global_store_dwordx4 v86, v[128:131], s[2:3]
	v_lshlrev_b32_e32 v89, 16, v100
	v_mul_f32_e32 v8, v8, v89
	v_and_b32_e32 v89, 0xffff0000, v100
	v_mul_f32_e32 v9, v9, v89
	v_lshlrev_b32_e32 v89, 16, v101
	v_mul_f32_e32 v10, v10, v89
	v_and_b32_e32 v89, 0xffff0000, v101
	v_mul_f32_e32 v11, v11, v89
	v_lshlrev_b32_e32 v89, 16, v102
	v_mul_f32_e32 v12, v12, v89
	v_and_b32_e32 v89, 0xffff0000, v102
	v_mul_f32_e32 v13, v13, v89
	v_lshlrev_b32_e32 v89, 16, v103
	v_mul_f32_e32 v14, v14, v89
	v_and_b32_e32 v89, 0xffff0000, v103
	v_mul_f32_e32 v15, v15, v89
	v_cvt_pk_bf16_f32 v132, v8, v9
	v_cvt_pk_bf16_f32 v133, v10, v11
	v_cvt_pk_bf16_f32 v134, v12, v13
	v_cvt_pk_bf16_f32 v135, v14, v15
	s_add_u32 s2, s2, 0x2000
	s_addc_u32 s3, s3, 0
	global_store_dwordx4 v86, v[132:135], s[2:3]
	v_lshlrev_b32_e32 v89, 16, v104
	v_mul_f32_e32 v16, v16, v89
	v_and_b32_e32 v89, 0xffff0000, v104
	v_mul_f32_e32 v17, v17, v89
	v_lshlrev_b32_e32 v89, 16, v105
	v_mul_f32_e32 v18, v18, v89
	v_and_b32_e32 v89, 0xffff0000, v105
	v_mul_f32_e32 v19, v19, v89
	v_lshlrev_b32_e32 v89, 16, v106
	v_mul_f32_e32 v20, v20, v89
	v_and_b32_e32 v89, 0xffff0000, v106
	v_mul_f32_e32 v21, v21, v89
	v_lshlrev_b32_e32 v89, 16, v107
	v_mul_f32_e32 v22, v22, v89
	v_and_b32_e32 v89, 0xffff0000, v107
	v_mul_f32_e32 v23, v23, v89
	v_cvt_pk_bf16_f32 v136, v16, v17
	v_cvt_pk_bf16_f32 v137, v18, v19
	v_cvt_pk_bf16_f32 v138, v20, v21
	v_cvt_pk_bf16_f32 v139, v22, v23
	s_add_u32 s2, s2, 0x2000
	s_addc_u32 s3, s3, 0
	global_store_dwordx4 v86, v[136:139], s[2:3]
	v_lshlrev_b32_e32 v89, 16, v108
	v_mul_f32_e32 v24, v24, v89
	v_and_b32_e32 v89, 0xffff0000, v108
	v_mul_f32_e32 v25, v25, v89
	v_lshlrev_b32_e32 v89, 16, v109
	v_mul_f32_e32 v26, v26, v89
	v_and_b32_e32 v89, 0xffff0000, v109
	v_mul_f32_e32 v27, v27, v89
	v_lshlrev_b32_e32 v89, 16, v110
	v_mul_f32_e32 v28, v28, v89
	v_and_b32_e32 v89, 0xffff0000, v110
	v_mul_f32_e32 v29, v29, v89
	v_lshlrev_b32_e32 v89, 16, v111
	v_mul_f32_e32 v30, v30, v89
	v_and_b32_e32 v89, 0xffff0000, v111
	v_mul_f32_e32 v31, v31, v89
	v_cvt_pk_bf16_f32 v140, v24, v25
	v_cvt_pk_bf16_f32 v141, v26, v27
	v_cvt_pk_bf16_f32 v142, v28, v29
	v_cvt_pk_bf16_f32 v143, v30, v31
	s_add_u32 s2, s2, 0x2000
	s_addc_u32 s3, s3, 0
	global_store_dwordx4 v86, v[140:143], s[2:3]
	v_lshlrev_b32_e32 v89, 16, v112
	v_mul_f32_e32 v32, v32, v89
	v_and_b32_e32 v89, 0xffff0000, v112
	v_mul_f32_e32 v33, v33, v89
	v_lshlrev_b32_e32 v89, 16, v113
	v_mul_f32_e32 v34, v34, v89
	v_and_b32_e32 v89, 0xffff0000, v113
	v_mul_f32_e32 v35, v35, v89
	v_lshlrev_b32_e32 v89, 16, v114
	v_mul_f32_e32 v36, v36, v89
	v_and_b32_e32 v89, 0xffff0000, v114
	v_mul_f32_e32 v37, v37, v89
	v_lshlrev_b32_e32 v89, 16, v115
	v_mul_f32_e32 v38, v38, v89
	v_and_b32_e32 v89, 0xffff0000, v115
	v_mul_f32_e32 v39, v39, v89
	v_cvt_pk_bf16_f32 v144, v32, v33
	v_cvt_pk_bf16_f32 v145, v34, v35
	v_cvt_pk_bf16_f32 v146, v36, v37
	v_cvt_pk_bf16_f32 v147, v38, v39
	s_add_u32 s2, s2, 0x2000
	s_addc_u32 s3, s3, 0
	global_store_dwordx4 v86, v[144:147], s[2:3]
	v_lshlrev_b32_e32 v89, 16, v116
	v_mul_f32_e32 v40, v40, v89
	v_and_b32_e32 v89, 0xffff0000, v116
	v_mul_f32_e32 v41, v41, v89
	v_lshlrev_b32_e32 v89, 16, v117
	v_mul_f32_e32 v42, v42, v89
	v_and_b32_e32 v89, 0xffff0000, v117
	v_mul_f32_e32 v43, v43, v89
	v_lshlrev_b32_e32 v89, 16, v118
	v_mul_f32_e32 v44, v44, v89
	v_and_b32_e32 v89, 0xffff0000, v118
	v_mul_f32_e32 v45, v45, v89
	v_lshlrev_b32_e32 v89, 16, v119
	v_mul_f32_e32 v46, v46, v89
	v_and_b32_e32 v89, 0xffff0000, v119
	v_mul_f32_e32 v47, v47, v89
	v_cvt_pk_bf16_f32 v148, v40, v41
	v_cvt_pk_bf16_f32 v149, v42, v43
	v_cvt_pk_bf16_f32 v150, v44, v45
	v_cvt_pk_bf16_f32 v151, v46, v47
	s_add_u32 s2, s2, 0x2000
	s_addc_u32 s3, s3, 0
	global_store_dwordx4 v86, v[148:151], s[2:3]
	v_lshlrev_b32_e32 v89, 16, v120
	v_mul_f32_e32 v48, v48, v89
	v_and_b32_e32 v89, 0xffff0000, v120
	v_mul_f32_e32 v49, v49, v89
	v_lshlrev_b32_e32 v89, 16, v121
	v_mul_f32_e32 v50, v50, v89
	v_and_b32_e32 v89, 0xffff0000, v121
	v_mul_f32_e32 v51, v51, v89
	v_lshlrev_b32_e32 v89, 16, v122
	v_mul_f32_e32 v52, v52, v89
	v_and_b32_e32 v89, 0xffff0000, v122
	v_mul_f32_e32 v53, v53, v89
	v_lshlrev_b32_e32 v89, 16, v123
	v_mul_f32_e32 v54, v54, v89
	v_and_b32_e32 v89, 0xffff0000, v123
	v_mul_f32_e32 v55, v55, v89
	v_cvt_pk_bf16_f32 v152, v48, v49
	v_cvt_pk_bf16_f32 v153, v50, v51
	v_cvt_pk_bf16_f32 v154, v52, v53
	v_cvt_pk_bf16_f32 v155, v54, v55
	s_add_u32 s2, s2, 0x2000
	s_addc_u32 s3, s3, 0
	global_store_dwordx4 v86, v[152:155], s[2:3]
	v_lshlrev_b32_e32 v89, 16, v124
	v_mul_f32_e32 v56, v56, v89
	v_and_b32_e32 v89, 0xffff0000, v124
	v_mul_f32_e32 v57, v57, v89
	v_lshlrev_b32_e32 v89, 16, v125
	v_mul_f32_e32 v58, v58, v89
	v_and_b32_e32 v89, 0xffff0000, v125
	v_mul_f32_e32 v59, v59, v89
	v_lshlrev_b32_e32 v89, 16, v126
	v_mul_f32_e32 v60, v60, v89
	v_and_b32_e32 v89, 0xffff0000, v126
	v_mul_f32_e32 v61, v61, v89
	v_lshlrev_b32_e32 v89, 16, v127
	v_mul_f32_e32 v62, v62, v89
	v_and_b32_e32 v89, 0xffff0000, v127
	v_mul_f32_e32 v63, v63, v89
	v_cvt_pk_bf16_f32 v156, v56, v57
	v_cvt_pk_bf16_f32 v157, v58, v59
	v_cvt_pk_bf16_f32 v158, v60, v61
	v_cvt_pk_bf16_f32 v159, v62, v63
	s_add_u32 s2, s2, 0x2000
	s_addc_u32 s3, s3, 0
	global_store_dwordx4 v86, v[156:159], s[2:3]
	s_waitcnt lgkmcnt(0)
	s_barrier
